# gMLP entry from the attention loop: no drain of the last item's stores before the first queue barrier
# speedup vs baseline: 1.0038x; 1.0038x over previous
.Lgq_379:
	s_or_b64 exec, exec, s[4:5]
	v_mov_b32_e32 v43, 0
	s_waitcnt lgkmcnt(0)
	s_barrier
	s_branch .Lgq_join

.Lgq_join:
	ds_read_b32 v1, v43 offset:8
	s_waitcnt lgkmcnt(0)
	v_readfirstlane_b32 s14, v1
	s_cmpk_gt_i32 s14, 0x1ff
	s_cbranch_scc1 .LBB0_396
	s_load_dwordx2 s[10:11], s[0:1], 0x90
	s_load_dwordx2 s[16:17], s[58:59], 0x0
	s_load_dwordx2 s[12:13], s[0:1], 0x30
	s_load_dwordx4 s[4:7], s[0:1], 0xc0
	s_mov_b32 s15, 0
	s_movk_i32 s3, 0x1a00
	s_waitcnt lgkmcnt(0)
	v_mov_b64_e32 v[44:45], s[16:17]
	s_movk_i32 s22, 0x90
	v_mbcnt_hi_u32_b32 v1, -1, v176
	s_branch .LBB0_382
